# scan: per-chunk y reduction of the 16 fp16 partials on the matrix core (4 x v_mfma_f32_16x16x32_f16 with a 0/1 selector) instead of 32 cvt + 15 pk_add per thread
# speedup vs baseline: 1.0025x; 1.0025x over previous
.LBB0_412:
	s_cmp_lg_u32 s93, 0
	s_cselect_b64 s[12:13], -1, 0
	s_and_b64 s[50:51], s[12:13], s[4:5]
	s_and_saveexec_b64 s[12:13], s[50:51]
	s_cbranch_execz .LBB0_414
	s_add_i32 s42, s93, -1
	s_lshl_b32 s50, s42, 14
	s_and_b32 s50, s50, 0x4000
	v_add_u32_e32 v32, s50, v105
	v_lshrrev_b32_e32 v134, 4, v152
	v_mul_u32_u24_e32 v134, 0x3f0, v134
	v_sub_u32_e32 v134, v32, v134
	ds_read_b128 v[116:119], v134 offset:45056
	ds_read_b128 v[120:123], v134 offset:46080
	ds_read_b128 v[124:127], v134 offset:47104
	ds_read_b128 v[24:27], v134 offset:48128
	v_and_b32_e32 v135, 15, v152
	v_mov_b32_e32 v130, 0
	v_mov_b32_e32 v131, 0x3c00
	v_cmp_eq_u32_e32 vcc, 0, v135
	v_mov_b32_e32 v132, 0x3c000000
	s_nop 1
	v_cndmask_b32_e32 v130, v130, v131, vcc
	v_cmp_eq_u32_e32 vcc, 1, v135
	s_nop 1
	v_cndmask_b32_e32 v130, v130, v132, vcc
	s_nop 0
	v_mov_b32_e32 v131, v130
	v_mov_b32_e32 v132, v130
	v_mov_b32_e32 v133, v130
	s_waitcnt lgkmcnt(3)
	v_mfma_f32_16x16x32_f16 v[28:31], v[130:133], v[116:119], 0
	s_waitcnt lgkmcnt(2)
	v_mfma_f32_16x16x32_f16 v[32:35], v[130:133], v[120:123], 0
	s_waitcnt lgkmcnt(1)
	v_mfma_f32_16x16x32_f16 v[116:119], v[130:133], v[124:127], 0
	s_waitcnt lgkmcnt(0)
	v_mfma_f32_16x16x32_f16 v[120:123], v[130:133], v[24:27], 0
	s_nop 1
	v_lshlrev_b32_e32 v42, 1, v40
	v_mov_b32_e32 v25, s11
	v_mov_b32_e32 v23, s33
	v_lshl_add_u32 v20, s42, 4, v46
	v_cmp_gt_i32_e32 vcc, s87, v20
	v_add_u32_e32 v22, 0xffffbf80, v20
	v_ashrrev_i32_e32 v21, 31, v20
	v_cndmask_b32_e32 v20, v22, v20, vcc
	v_mov_b32_e32 v22, s10
	v_cndmask_b32_e32 v21, 0, v21, vcc
	v_cndmask_b32_e32 v23, v22, v23, vcc
	v_mov_b32_e32 v22, s3
	v_cndmask_b32_e32 v22, v22, v25, vcc
	v_lshlrev_b64 v[20:21], 11, v[20:21]
	v_lshl_add_u64 v[20:21], v[22:23], 0, v[20:21]
	s_lshl_b32 s42, s57, 1
	v_lshl_add_u64 v[20:21], v[20:21], 0, s[42:43]
	s_lshl_b32 s42, s92, 1
	v_lshl_add_u64 v[20:21], v[20:21], 0, s[42:43]
	v_lshl_add_u64 v[20:21], v[20:21], 0, v[42:43]
	s_movk_i32 s42, 0x1000
	v_lshl_add_u64 v[20:21], v[20:21], 0, s[42:43]
	v_cvt_pk_f16_f32 v28, v28, v29
	v_cvt_pk_f16_f32 v32, v32, v33
	v_cvt_pk_f16_f32 v116, v116, v117
	v_cvt_pk_f16_f32 v120, v120, v121
	s_mov_b64 s[50:51], exec
	s_mov_b64 exec, 0xffff
	global_store_dword v[20:21], v28, off offset:-4096
	global_store_dword v[20:21], v32, off offset:-2048
	global_store_dword v[20:21], v116, off
	global_store_dword v[20:21], v120, off offset:2048
	s_mov_b64 exec, s[50:51]

.LBB0_423:
	s_and_saveexec_b64 s[12:13], s[4:5]
	s_cbranch_execz .LBB0_425
	s_mulk_i32 s42, 0xe800
	s_add_i32 s97, s97, s42
	v_add3_u32 v42, s97, v103, v104
	v_lshrrev_b32_e32 v134, 4, v152
	v_mul_u32_u24_e32 v134, 0x3f0, v134
	v_sub_u32_e32 v134, v42, v134
	ds_read_b128 v[116:119], v134 offset:45056
	ds_read_b128 v[120:123], v134 offset:46080
	ds_read_b128 v[124:127], v134 offset:47104
	ds_read_b128 v[28:31], v134 offset:48128
	v_and_b32_e32 v135, 15, v152
	v_mov_b32_e32 v130, 0
	v_mov_b32_e32 v131, 0x3c00
	v_cmp_eq_u32_e32 vcc, 0, v135
	v_mov_b32_e32 v132, 0x3c000000
	s_nop 1
	v_cndmask_b32_e32 v130, v130, v131, vcc
	v_cmp_eq_u32_e32 vcc, 1, v135
	s_nop 1
	v_cndmask_b32_e32 v130, v130, v132, vcc
	s_nop 0
	v_mov_b32_e32 v131, v130
	v_mov_b32_e32 v132, v130
	v_mov_b32_e32 v133, v130
	s_waitcnt lgkmcnt(3)
	v_mfma_f32_16x16x32_f16 v[90:93], v[130:133], v[116:119], 0
	s_waitcnt lgkmcnt(2)
	v_mfma_f32_16x16x32_f16 v[32:35], v[130:133], v[120:123], 0
	s_waitcnt lgkmcnt(1)
	v_mfma_f32_16x16x32_f16 v[116:119], v[130:133], v[124:127], 0
	s_waitcnt lgkmcnt(0)
	v_mfma_f32_16x16x32_f16 v[120:123], v[130:133], v[28:31], 0
	s_nop 1
	s_lshl_b32 s42, s57, 1
	v_lshlrev_b32_e32 v42, 1, v40
	v_mov_b32_e32 v29, s11
	v_mov_b32_e32 v27, s33
	v_add_u32_e32 v24, s94, v46
	v_cmp_gt_i32_e32 vcc, s87, v24
	v_add_u32_e32 v26, 0xffffbf80, v24
	v_ashrrev_i32_e32 v25, 31, v24
	v_cndmask_b32_e32 v24, v26, v24, vcc
	v_mov_b32_e32 v26, s10
	v_cndmask_b32_e32 v25, 0, v25, vcc
	v_cndmask_b32_e32 v27, v26, v27, vcc
	v_mov_b32_e32 v26, s3
	v_cndmask_b32_e32 v26, v26, v29, vcc
	v_lshlrev_b64 v[24:25], 11, v[24:25]
	v_lshl_add_u64 v[24:25], v[26:27], 0, v[24:25]
	v_lshl_add_u64 v[24:25], v[24:25], 0, s[42:43]
	s_lshl_b32 s42, s92, 1
	v_lshl_add_u64 v[24:25], v[24:25], 0, s[42:43]
	v_lshl_add_u64 v[24:25], v[24:25], 0, v[42:43]
	s_movk_i32 s42, 0x1000
	v_lshl_add_u64 v[24:25], v[24:25], 0, s[42:43]
	v_cvt_pk_f16_f32 v90, v90, v91
	v_cvt_pk_f16_f32 v32, v32, v33
	v_cvt_pk_f16_f32 v116, v116, v117
	v_cvt_pk_f16_f32 v120, v120, v121
	s_mov_b64 s[50:51], exec
	s_mov_b64 exec, 0xffff
	global_store_dword v[24:25], v90, off offset:-4096
	global_store_dword v[24:25], v32, off offset:-2048
	global_store_dword v[24:25], v116, off
	global_store_dword v[24:25], v120, off offset:2048
	s_mov_b64 exec, s[50:51]

.LBB0_434:
	s_and_saveexec_b64 s[12:13], s[4:5]
	s_cbranch_execz .LBB0_436
	s_lshl_b32 s42, s96, 14
	s_and_b32 s42, s42, 0x4000
	v_add_u32_e32 v30, s42, v105
	v_lshrrev_b32_e32 v134, 4, v152
	v_mul_u32_u24_e32 v134, 0x3f0, v134
	v_sub_u32_e32 v134, v30, v134
	ds_read_b128 v[116:119], v134 offset:45056
	ds_read_b128 v[120:123], v134 offset:46080
	ds_read_b128 v[124:127], v134 offset:47104
	ds_read_b128 v[20:23], v134 offset:48128
	v_and_b32_e32 v135, 15, v152
	v_mov_b32_e32 v130, 0
	v_mov_b32_e32 v131, 0x3c00
	v_cmp_eq_u32_e32 vcc, 0, v135
	v_mov_b32_e32 v132, 0x3c000000
	s_nop 1
	v_cndmask_b32_e32 v130, v130, v131, vcc
	v_cmp_eq_u32_e32 vcc, 1, v135
	s_nop 1
	v_cndmask_b32_e32 v130, v130, v132, vcc
	s_nop 0
	v_mov_b32_e32 v131, v130
	v_mov_b32_e32 v132, v130
	v_mov_b32_e32 v133, v130
	s_waitcnt lgkmcnt(3)
	v_mfma_f32_16x16x32_f16 v[24:27], v[130:133], v[116:119], 0
	s_waitcnt lgkmcnt(2)
	v_mfma_f32_16x16x32_f16 v[92:95], v[130:133], v[120:123], 0
	s_waitcnt lgkmcnt(1)
	v_mfma_f32_16x16x32_f16 v[116:119], v[130:133], v[124:127], 0
	s_waitcnt lgkmcnt(0)
	v_mfma_f32_16x16x32_f16 v[120:123], v[130:133], v[20:23], 0
	s_nop 1
	s_lshl_b32 s42, s57, 1
	v_lshlrev_b32_e32 v42, 1, v40
	v_mov_b32_e32 v21, s11
	v_mov_b32_e32 v19, s33
	v_add_u32_e32 v16, s95, v46
	v_cmp_gt_i32_e32 vcc, s87, v16
	v_add_u32_e32 v18, 0xffffbf80, v16
	v_ashrrev_i32_e32 v17, 31, v16
	v_cndmask_b32_e32 v16, v18, v16, vcc
	v_mov_b32_e32 v18, s10
	v_cndmask_b32_e32 v17, 0, v17, vcc
	v_cndmask_b32_e32 v19, v18, v19, vcc
	v_mov_b32_e32 v18, s3
	v_cndmask_b32_e32 v18, v18, v21, vcc
	v_lshlrev_b64 v[16:17], 11, v[16:17]
	v_lshl_add_u64 v[16:17], v[18:19], 0, v[16:17]
	v_lshl_add_u64 v[16:17], v[16:17], 0, s[42:43]
	s_lshl_b32 s42, s92, 1
	v_lshl_add_u64 v[16:17], v[16:17], 0, s[42:43]
	v_lshl_add_u64 v[16:17], v[16:17], 0, v[42:43]
	s_movk_i32 s42, 0x1000
	v_lshl_add_u64 v[16:17], v[16:17], 0, s[42:43]
	v_cvt_pk_f16_f32 v24, v24, v25
	v_cvt_pk_f16_f32 v92, v92, v93
	v_cvt_pk_f16_f32 v116, v116, v117
	v_cvt_pk_f16_f32 v120, v120, v121
	s_mov_b64 s[50:51], exec
	s_mov_b64 exec, 0xffff
	global_store_dword v[16:17], v24, off offset:-4096
	global_store_dword v[16:17], v92, off offset:-2048
	global_store_dword v[16:17], v116, off
	global_store_dword v[16:17], v120, off offset:2048
	s_mov_b64 exec, s[50:51]
